# K-loop: per-block s_setprio flips removed, one static s_setprio 1 for the trailing half (waves 4-7) per GEMM phase
# speedup vs baseline: 1.0028x; 1.0028x over previous
; __device__ __forceinline__ int TID() { int t = threadIdx.x; asm volatile("" : "+v"(t)); return t; }
; #define PG8_STAGE(bufoff, gbase, voff) do { _Pragma("unroll") for (int _i = 0; _i < 2; ++_i) \
;         __builtin_amdgcn_global_load_lds((const unsigned*)((const char*)(gbase) + (voff)[_i]), (PG8_LAS unsigned*)(lds + (bufoff) + ldsw + _i * 8192), 16, 0, 0); } while (0)
; #define PG8_WAIT_V(n) asm volatile("s_waitcnt vmcnt(" #n ")" ::: "memory")
; #define PG8_BAR __builtin_amdgcn_s_barrier()
; template <class Epi, class Sched, bool ALIGN_EPI = false, bool SP2 = false>
; __device__ __forceinline__ void gemm_phase(PG8_LAS unsigned char* lds, const Gemm g, const Sched& S, const Epi& E) {
;     const int tid = TID(), wid = __builtin_amdgcn_readfirstlane(tid >> 6), lane = tid & 63, wr = wid >> 2, wc = wid & 3, fr = lane & 15, fq = lane >> 4;
;     const int K = g.K, nt = K / BK;
;     unsigned voffA[2], voffB[2];
; #pragma unroll
;     for (int i = 0; i < 2; ++i) { int R, C; stage_rc(tid * 16 + i * 8192, R, C); const int Rb = Epi::PERM ? ((R & ~31) + perm32(R & 31)) : R;
;         voffA[i] = (unsigned)(R * K + C) * 2u; voffB[i] = (unsigned)(Rb * K + C) * 2u; }
;     const size_t kstep = (size_t)(BK * 2);
;     const size_t hstep = (size_t)HALF * K * 2;
;     const size_t tstep = 2 * hstep;
;     const unsigned ldsw = (unsigned)wid * 1024u;
;     const int aoff = lds_byte(wr * 64 + fr, fq * 8), boff = lds_byte(wc * 32 + fr, fq * 8);
;     ...
;         if (wr == 1) PG8_BAR;
;         PG8_WAIT_V(2); PG8_BAR;
;         PG8_STAGE(PG8_SB(1, 0), cB + kstep, voffB); PG8_STAGE(PG8_SA(1, 0), cA + kstep, voffA); PG8_STAGE(PG8_SB(1, 1), cB + hstep + kstep, voffB);
;         PG8_WAIT_V(6); PG8_BAR;
;     } else {
;         PG8_STAGE(PG8_SB(0, 0), cB, voffB); PG8_STAGE(PG8_SA(0, 0), cA, voffA); PG8_STAGE(PG8_SB(0, 1), cB + hstep, voffB); PG8_STAGE(PG8_SA(0, 1), cA + hstep, voffA);
;         if (wr == 1) PG8_BAR;
;         PG8_WAIT_V(4); PG8_BAR;
.LBB0_701:
	s_waitcnt vmcnt(8)
	s_barrier
	v_lshrrev_b32_e32 v2, 1, v0
	v_and_b32_e32 v2, 24, v2
	v_and_b32_e32 v3, 15, v0
	v_lshlrev_b32_e32 v4, 1, v2
	v_lshlrev_b32_e32 v0, 2, v0
	v_lshl_or_b32 v4, v3, 6, v4
	s_lshl_b32 s11, s21, 13
	v_and_b32_e32 v0, 32, v0
	s_and_b32 s9, s9, 0x60
	v_bitop3_b32 v5, v4, s11, v0 bitop3:0xde
	s_lshl_b32 s11, s9, 7
	s_add_i32 s57, s56, -2
	s_cmpk_lt_u32 s8, 0x100
	s_cselect_b64 s[40:41], -1, 0
	s_lshl_b32 s58, s10, 3
	v_bitop3_b32 v211, v4, s11, v0 bitop3:0xde
	v_cvt_f32_u32_e32 v0, s58
	s_sub_i32 s8, 0, s58
	s_waitcnt vmcnt(6)
	v_lshl_or_b32 v210, s21, 6, v3
	v_rcp_iflag_f32_e32 v0, v0
	s_mov_b32 s59, 0
	v_cmp_eq_u32_e64 s[42:43], 0, v3
	s_ashr_i32 s60, s20, 31
	v_mul_f32_e32 v0, 0x4f7ffffe, v0
	v_cvt_u32_f32_e32 v0, v0
	s_mov_b32 s29, s97
	s_lshr_b32 s61, s28, 3
	v_or_b32_e32 v212, s9, v2
	v_readfirstlane_b32 s10, v0
	v_add_u32_e32 v0, v16, v14
	v_add_lshl_u32 v0, v0, v15, 1
	s_mul_i32 s8, s8, s10
	v_lshl_add_u64 v[174:175], s[96:97], 0, v[0:1]
	v_add_u32_e32 v0, v19, v17
	s_mul_hi_u32 s8, s10, s8
	v_add_lshl_u32 v0, v0, v18, 1
	s_add_i32 s62, s10, s8
	v_lshl_add_u64 v[176:177], s[96:97], 0, v[0:1]
	v_add_u32_e32 v214, 0, v5
	s_lshl_b32 s64, s9, 1
	v_lshlrev_b32_e32 v178, 1, v2
	s_barrier
	s_cmp_lg_u32 s21, 1
	s_cbranch_scc1 .Lprio_skip
	s_setprio 1
.Lprio_skip:
	s_branch .LBB0_704

; #define PG8_STAGE(bufoff, gbase, voff) do { _Pragma("unroll") for (int _i = 0; _i < 2; ++_i) \
;         __builtin_amdgcn_global_load_lds((const unsigned*)((const char*)(gbase) + (voff)[_i]), (PG8_LAS unsigned*)(lds + (bufoff) + ldsw + _i * 8192), 16, 0, 0); } while (0)
; #define PG8_LDA(dst, b, h) do { _Pragma("unroll") for (int m = 0; m < 4; ++m) _Pragma("unroll") for (int k = 0; k < 2; ++k) dst[m][k] = *(const PG8_LAS bf16x8*)(lds + PG8_SA(b, h) + aoff + m * 2048 + k * 1024); } while (0)
; #define PG8_LDB(dst, b, h) do { _Pragma("unroll") for (int n = 0; n < 2; ++n) _Pragma("unroll") for (int k = 0; k < 2; ++k) dst[n][k] = *(const PG8_LAS bf16x8*)(lds + PG8_SB(b, h) + boff + n * 2048 + k * 1024); } while (0)
; #define PG8_MMA(ai, bj, At, Bt) do { __builtin_amdgcn_s_setprio(1); _Pragma("unroll") for (int m = 0; m < 4; ++m) _Pragma("unroll") for (int n = 0; n < 2; ++n) _Pragma("unroll") for (int k = 0; k < 2; ++k) \
;         acc[ai][bj][m][n] = __builtin_amdgcn_mfma_f32_16x16x32_bf16(Bt[n][k], At[m][k], acc[ai][bj][m][n], 0, 0, 0); __builtin_amdgcn_s_setprio(0); } while (0)
; #define PG8_WAIT_V(n) asm volatile("s_waitcnt vmcnt(" #n ")" ::: "memory")
; #define PG8_WAIT_L(n) asm volatile("s_waitcnt lgkmcnt(" #n ")" ::: "memory")
; #define PG8_BAR __builtin_amdgcn_s_barrier()
; #define PG8_SCHED __builtin_amdgcn_sched_barrier(0)
; template <class Epi, class Sched, bool ALIGN_EPI = false, bool SP2 = false>
; __device__ __forceinline__ void gemm_phase(PG8_LAS unsigned char* lds, const Gemm g, const Sched& S, const Epi& E) {
;     ...
;             PG8_LDB(B0, 0, 0); PG8_LDB(B1, 0, 1); PG8_SCHED; PG8_LDA(At, 0, 0); PG8_STAGE(PG8_SA(1, 1), a1 + hstep, voffA);
;             PG8_WAIT_V(8); PG8_WAIT_L(0); PG8_BAR; PG8_MMA(0, 0, At, B0); PG8_MMA(0, 1, At, B1); PG8_BAR; PG8_SCHED;
;             PG8_LDA(At, 0, 1); PG8_STAGE(PG8_SB(0, 0), b2, voffB); PG8_STAGE(PG8_SB(0, 1), b2 + hstep, voffB); PG8_STAGE(PG8_SA(0, 0), a2, voffA);
;             PG8_WAIT_V(8); PG8_WAIT_L(0); PG8_BAR; PG8_MMA(1, 0, At, B0); PG8_MMA(1, 1, At, B1); PG8_BAR; PG8_SCHED;
.LBB0_710:
	s_add_u32 s2, s2, 0x80
	s_addc_u32 s3, s3, 0
	s_add_u32 s8, s6, 0x100
	s_addc_u32 s9, s7, 0
	s_mov_b32 s6, 0
	s_add_i32 s10, s6, 2
	s_add_u32 s11, s2, 0x80
	s_addc_u32 s7, s3, 0
	s_waitcnt lgkmcnt(0)
	s_add_i32 s52, 0, 0x10000
	v_add_u32_e32 v0, s52, v211
	ds_read_b128 v[130:133], v0
	ds_read_b128 v[134:137], v0 offset:1024
	ds_read_b128 v[138:141], v0 offset:2048
	ds_read_b128 v[142:145], v0 offset:3072
	v_add_u32_e32 v0, s87, v211
	ds_read_b128 v[146:149], v0
	ds_read_b128 v[150:153], v0 offset:1024
	ds_read_b128 v[154:157], v0 offset:2048
	ds_read_b128 v[158:161], v0 offset:3072
	s_cmp_eq_u32 s57, s6
	s_cselect_b32 s6, s48, s11
	s_cselect_b32 s7, s49, s7
	s_cselect_b32 s47, s51, s9
	s_cselect_b32 s46, s50, s8
	v_lshl_add_u64 v[208:209], s[2:3], 0, v[174:175]
	s_add_i32 m0, s23, 0xc000
	ds_read_b128 v[162:165], v214
	ds_read_b128 v[180:183], v214 offset:1024
	ds_read_b128 v[184:187], v214 offset:2048
	ds_read_b128 v[188:191], v214 offset:3072
	ds_read_b128 v[192:195], v214 offset:4096
	ds_read_b128 v[196:199], v214 offset:5120
	ds_read_b128 v[200:203], v214 offset:6144
	ds_read_b128 v[204:207], v214 offset:7168
	global_load_lds_dwordx4 v[208:209], off
	v_lshl_add_u64 v[208:209], s[2:3], 0, v[176:177]
	s_add_i32 m0, s23, 0xe000
	s_nop 0
	global_load_lds_dwordx4 v[208:209], off
	s_waitcnt vmcnt(8)
	s_waitcnt lgkmcnt(0)
	s_barrier
	s_waitcnt lgkmcnt(0)
	v_mfma_f32_16x16x32_bf16 v[126:129], v[130:133], v[162:165], 0
	v_mfma_f32_16x16x32_bf16 v[122:125], v[138:141], v[162:165], 0
	v_mfma_f32_16x16x32_bf16 v[118:121], v[130:133], v[184:187], 0
	v_mfma_f32_16x16x32_bf16 v[110:113], v[138:141], v[184:187], 0
	v_mfma_f32_16x16x32_bf16 v[102:105], v[130:133], v[192:195], 0
	v_mfma_f32_16x16x32_bf16 v[94:97], v[138:141], v[192:195], 0
	v_mfma_f32_16x16x32_bf16 v[86:89], v[130:133], v[200:203], 0
	v_mfma_f32_16x16x32_bf16 v[78:81], v[138:141], v[200:203], 0
	v_mfma_f32_16x16x32_bf16 v[126:129], v[134:137], v[180:183], v[126:129]
	v_mfma_f32_16x16x32_bf16 v[122:125], v[142:145], v[180:183], v[122:125]
	v_mfma_f32_16x16x32_bf16 v[118:121], v[134:137], v[188:191], v[118:121]
	v_mfma_f32_16x16x32_bf16 v[110:113], v[142:145], v[188:191], v[110:113]
	v_mfma_f32_16x16x32_bf16 v[102:105], v[134:137], v[196:199], v[102:105]
	v_mfma_f32_16x16x32_bf16 v[94:97], v[142:145], v[196:199], v[94:97]
	v_mfma_f32_16x16x32_bf16 v[86:89], v[134:137], v[204:207], v[86:89]
	v_mfma_f32_16x16x32_bf16 v[78:81], v[142:145], v[204:207], v[78:81]
	v_mfma_f32_16x16x32_bf16 v[114:117], v[146:149], v[162:165], 0
	v_mfma_f32_16x16x32_bf16 v[106:109], v[154:157], v[162:165], 0
	v_mfma_f32_16x16x32_bf16 v[98:101], v[146:149], v[184:187], 0
	v_mfma_f32_16x16x32_bf16 v[90:93], v[154:157], v[184:187], 0
	v_mfma_f32_16x16x32_bf16 v[82:85], v[146:149], v[192:195], 0
	v_mfma_f32_16x16x32_bf16 v[74:77], v[154:157], v[192:195], 0
	v_mfma_f32_16x16x32_bf16 v[70:73], v[146:149], v[200:203], 0
	v_mfma_f32_16x16x32_bf16 v[66:69], v[154:157], v[200:203], 0
	v_mfma_f32_16x16x32_bf16 v[114:117], v[150:153], v[180:183], v[114:117]
	v_mfma_f32_16x16x32_bf16 v[106:109], v[158:161], v[180:183], v[106:109]
	v_mfma_f32_16x16x32_bf16 v[98:101], v[150:153], v[188:191], v[98:101]
	v_mfma_f32_16x16x32_bf16 v[90:93], v[158:161], v[188:191], v[90:93]
	v_mfma_f32_16x16x32_bf16 v[82:85], v[150:153], v[196:199], v[82:85]
	v_mfma_f32_16x16x32_bf16 v[74:77], v[158:161], v[196:199], v[74:77]
	v_mfma_f32_16x16x32_bf16 v[70:73], v[150:153], v[204:207], v[70:73]
	v_mfma_f32_16x16x32_bf16 v[66:69], v[158:161], v[204:207], v[66:69]
	s_barrier
	s_add_i32 s11, s52, s22
	v_lshl_add_u64 v[208:209], s[46:47], 0, v[168:169]
	s_mov_b32 m0, s11
	ds_read_b128 v[162:165], v214 offset:16384
	ds_read_b128 v[180:183], v214 offset:17408
	ds_read_b128 v[184:187], v214 offset:18432
	ds_read_b128 v[188:191], v214 offset:19456
	ds_read_b128 v[192:195], v214 offset:20480
	ds_read_b128 v[196:199], v214 offset:21504
	ds_read_b128 v[200:203], v214 offset:22528
	ds_read_b128 v[204:207], v214 offset:23552
	global_load_lds_dwordx4 v[208:209], off
	s_add_i32 m0, s11, 0x2000
	v_lshl_add_u64 v[216:217], s[46:47], 0, v[172:173]
	s_add_u32 s46, s46, s96
	s_addc_u32 s47, s47, 0
	s_add_i32 s11, s87, s22
	global_load_lds_dwordx4 v[216:217], off
	v_lshl_add_u64 v[220:221], s[46:47], 0, v[168:169]
	s_mov_b32 m0, s11
	v_lshl_add_u64 v[224:225], s[46:47], 0, v[172:173]
	global_load_lds_dwordx4 v[220:221], off
	s_add_i32 m0, s11, 0x2000
	v_lshl_add_u64 v[228:229], s[6:7], 0, v[166:167]
	global_load_lds_dwordx4 v[224:225], off
	s_mov_b32 m0, s23
	v_lshl_add_u64 v[230:231], s[6:7], 0, v[170:171]
	global_load_lds_dwordx4 v[228:229], off
	s_mov_b32 m0, s24
	s_nop 0
	global_load_lds_dwordx4 v[230:231], off
	s_waitcnt vmcnt(8)
	s_waitcnt lgkmcnt(0)
	s_barrier
; #define PG8_STAGE(bufoff, gbase, voff) do { _Pragma("unroll") for (int _i = 0; _i < 2; ++_i) \
;         __builtin_amdgcn_global_load_lds((const unsigned*)((const char*)(gbase) + (voff)[_i]), (PG8_LAS unsigned*)(lds + (bufoff) + ldsw + _i * 8192), 16, 0, 0); } while (0)
; #define PG8_LDA(dst, b, h) do { _Pragma("unroll") for (int m = 0; m < 4; ++m) _Pragma("unroll") for (int k = 0; k < 2; ++k) dst[m][k] = *(const PG8_LAS bf16x8*)(lds + PG8_SA(b, h) + aoff + m * 2048 + k * 1024); } while (0)
; #define PG8_LDB(dst, b, h) do { _Pragma("unroll") for (int n = 0; n < 2; ++n) _Pragma("unroll") for (int k = 0; k < 2; ++k) dst[n][k] = *(const PG8_LAS bf16x8*)(lds + PG8_SB(b, h) + boff + n * 2048 + k * 1024); } while (0)
; #define PG8_MMA(ai, bj, At, Bt) do { __builtin_amdgcn_s_setprio(1); _Pragma("unroll") for (int m = 0; m < 4; ++m) _Pragma("unroll") for (int n = 0; n < 2; ++n) _Pragma("unroll") for (int k = 0; k < 2; ++k) \
;         acc[ai][bj][m][n] = __builtin_amdgcn_mfma_f32_16x16x32_bf16(Bt[n][k], At[m][k], acc[ai][bj][m][n], 0, 0, 0); __builtin_amdgcn_s_setprio(0); } while (0)
; #define PG8_WAIT_V(n) asm volatile("s_waitcnt vmcnt(" #n ")" ::: "memory")
; #define PG8_WAIT_L(n) asm volatile("s_waitcnt lgkmcnt(" #n ")" ::: "memory")
; #define PG8_BAR __builtin_amdgcn_s_barrier()
; #define PG8_SCHED __builtin_amdgcn_sched_barrier(0)
; template <class Epi, class Sched, bool ALIGN_EPI = false, bool SP2 = false>
; __device__ __forceinline__ void gemm_phase(PG8_LAS unsigned char* lds, const Gemm g, const Sched& S, const Epi& E) {
;     ...
;             PG8_WAIT_V(8); PG8_WAIT_L(0); PG8_BAR; PG8_MMA(1, 0, At, B0); PG8_MMA(1, 1, At, B1); PG8_BAR; PG8_SCHED;
;             PG8_LDB(B0, 1, 0); PG8_LDB(B1, 1, 1); PG8_SCHED; PG8_LDA(At, 1, 0); PG8_STAGE(PG8_SA(0, 1), a2 + hstep, voffA);
;             PG8_WAIT_V(8); PG8_WAIT_L(0); PG8_BAR; PG8_MMA(0, 0, At, B0); PG8_MMA(0, 1, At, B1); PG8_BAR; PG8_SCHED;
	s_waitcnt lgkmcnt(0)
	v_mfma_f32_16x16x32_bf16 v[62:65], v[130:133], v[162:165], 0
	v_mfma_f32_16x16x32_bf16 v[58:61], v[138:141], v[162:165], 0
	v_mfma_f32_16x16x32_bf16 v[54:57], v[130:133], v[184:187], 0
	v_mfma_f32_16x16x32_bf16 v[46:49], v[138:141], v[184:187], 0
	v_mfma_f32_16x16x32_bf16 v[38:41], v[130:133], v[192:195], 0
	v_mfma_f32_16x16x32_bf16 v[30:33], v[138:141], v[192:195], 0
	v_mfma_f32_16x16x32_bf16 v[22:25], v[130:133], v[200:203], 0
	v_mfma_f32_16x16x32_bf16 v[14:17], v[138:141], v[200:203], 0
	v_mfma_f32_16x16x32_bf16 v[62:65], v[134:137], v[180:183], v[62:65]
	v_mfma_f32_16x16x32_bf16 v[58:61], v[142:145], v[180:183], v[58:61]
	v_mfma_f32_16x16x32_bf16 v[54:57], v[134:137], v[188:191], v[54:57]
	v_mfma_f32_16x16x32_bf16 v[46:49], v[142:145], v[188:191], v[46:49]
	v_mfma_f32_16x16x32_bf16 v[38:41], v[134:137], v[196:199], v[38:41]
	v_mfma_f32_16x16x32_bf16 v[30:33], v[142:145], v[196:199], v[30:33]
	v_mfma_f32_16x16x32_bf16 v[22:25], v[134:137], v[204:207], v[22:25]
	v_mfma_f32_16x16x32_bf16 v[14:17], v[142:145], v[204:207], v[14:17]
	v_mfma_f32_16x16x32_bf16 v[50:53], v[146:149], v[162:165], 0
	v_mfma_f32_16x16x32_bf16 v[42:45], v[154:157], v[162:165], 0
	v_mfma_f32_16x16x32_bf16 v[34:37], v[146:149], v[184:187], 0
	v_mfma_f32_16x16x32_bf16 v[26:29], v[154:157], v[184:187], 0
	v_mfma_f32_16x16x32_bf16 v[18:21], v[146:149], v[192:195], 0
	v_mfma_f32_16x16x32_bf16 v[10:13], v[154:157], v[192:195], 0
	v_mfma_f32_16x16x32_bf16 v[6:9], v[146:149], v[200:203], 0
	v_mfma_f32_16x16x32_bf16 v[2:5], v[154:157], v[200:203], 0
	v_mfma_f32_16x16x32_bf16 v[50:53], v[150:153], v[180:183], v[50:53]
	v_mfma_f32_16x16x32_bf16 v[42:45], v[158:161], v[180:183], v[42:45]
	v_mfma_f32_16x16x32_bf16 v[34:37], v[150:153], v[188:191], v[34:37]
	v_mfma_f32_16x16x32_bf16 v[26:29], v[158:161], v[188:191], v[26:29]
	v_mfma_f32_16x16x32_bf16 v[18:21], v[150:153], v[196:199], v[18:21]
	v_mfma_f32_16x16x32_bf16 v[10:13], v[158:161], v[196:199], v[10:13]
	v_mfma_f32_16x16x32_bf16 v[6:9], v[150:153], v[204:207], v[6:9]
	v_mfma_f32_16x16x32_bf16 v[2:5], v[158:161], v[204:207], v[2:5]
	s_barrier
	s_add_i32 s11, 0, 0x18000
	v_add_u32_e32 v0, s11, v211
	ds_read_b128 v[130:133], v0
	ds_read_b128 v[134:137], v0 offset:1024
	ds_read_b128 v[138:141], v0 offset:2048
	ds_read_b128 v[142:145], v0 offset:3072
	v_add_u32_e32 v0, s86, v211
	ds_read_b128 v[146:149], v0
	ds_read_b128 v[150:153], v0 offset:1024
	ds_read_b128 v[154:157], v0 offset:2048
	ds_read_b128 v[158:161], v0 offset:3072
	s_add_u32 s6, s6, s96
	s_addc_u32 s7, s7, 0
	s_mov_b32 m0, s25
	v_lshl_add_u64 v[238:239], s[6:7], 0, v[166:167]
	ds_read_b128 v[162:165], v214 offset:32768
	ds_read_b128 v[180:183], v214 offset:33792
	ds_read_b128 v[184:187], v214 offset:34816
	ds_read_b128 v[188:191], v214 offset:35840
	ds_read_b128 v[192:195], v214 offset:36864
	ds_read_b128 v[196:199], v214 offset:37888
	ds_read_b128 v[200:203], v214 offset:38912
	ds_read_b128 v[204:207], v214 offset:39936
	global_load_lds_dwordx4 v[238:239], off
	v_lshl_add_u64 v[238:239], s[6:7], 0, v[170:171]
	s_mov_b32 m0, s27
	s_nop 0
	global_load_lds_dwordx4 v[238:239], off
	s_waitcnt vmcnt(8)
	s_waitcnt lgkmcnt(0)
	s_barrier
	s_waitcnt lgkmcnt(0)
	v_mfma_f32_16x16x32_bf16 v[126:129], v[130:133], v[162:165], v[126:129]
	v_mfma_f32_16x16x32_bf16 v[122:125], v[138:141], v[162:165], v[122:125]
	v_mfma_f32_16x16x32_bf16 v[118:121], v[130:133], v[184:187], v[118:121]
	v_mfma_f32_16x16x32_bf16 v[110:113], v[138:141], v[184:187], v[110:113]
	v_mfma_f32_16x16x32_bf16 v[102:105], v[130:133], v[192:195], v[102:105]
	v_mfma_f32_16x16x32_bf16 v[94:97], v[138:141], v[192:195], v[94:97]
	v_mfma_f32_16x16x32_bf16 v[86:89], v[130:133], v[200:203], v[86:89]
	v_mfma_f32_16x16x32_bf16 v[78:81], v[138:141], v[200:203], v[78:81]
	v_mfma_f32_16x16x32_bf16 v[126:129], v[134:137], v[180:183], v[126:129]
	v_mfma_f32_16x16x32_bf16 v[122:125], v[142:145], v[180:183], v[122:125]
	v_mfma_f32_16x16x32_bf16 v[118:121], v[134:137], v[188:191], v[118:121]
	v_mfma_f32_16x16x32_bf16 v[110:113], v[142:145], v[188:191], v[110:113]
	v_mfma_f32_16x16x32_bf16 v[102:105], v[134:137], v[196:199], v[102:105]
	v_mfma_f32_16x16x32_bf16 v[94:97], v[142:145], v[196:199], v[94:97]
	v_mfma_f32_16x16x32_bf16 v[86:89], v[134:137], v[204:207], v[86:89]
	v_mfma_f32_16x16x32_bf16 v[78:81], v[142:145], v[204:207], v[78:81]
	v_mfma_f32_16x16x32_bf16 v[114:117], v[146:149], v[162:165], v[114:117]
	v_mfma_f32_16x16x32_bf16 v[106:109], v[154:157], v[162:165], v[106:109]
	v_mfma_f32_16x16x32_bf16 v[98:101], v[146:149], v[184:187], v[98:101]
	v_mfma_f32_16x16x32_bf16 v[90:93], v[154:157], v[184:187], v[90:93]
	v_mfma_f32_16x16x32_bf16 v[82:85], v[146:149], v[192:195], v[82:85]
	v_mfma_f32_16x16x32_bf16 v[74:77], v[154:157], v[192:195], v[74:77]
	v_mfma_f32_16x16x32_bf16 v[70:73], v[146:149], v[200:203], v[70:73]
	v_mfma_f32_16x16x32_bf16 v[66:69], v[154:157], v[200:203], v[66:69]
	v_mfma_f32_16x16x32_bf16 v[114:117], v[150:153], v[180:183], v[114:117]
	v_mfma_f32_16x16x32_bf16 v[106:109], v[158:161], v[180:183], v[106:109]
	v_mfma_f32_16x16x32_bf16 v[98:101], v[150:153], v[188:191], v[98:101]
	v_mfma_f32_16x16x32_bf16 v[90:93], v[158:161], v[188:191], v[90:93]
	v_mfma_f32_16x16x32_bf16 v[82:85], v[150:153], v[196:199], v[82:85]
	v_mfma_f32_16x16x32_bf16 v[74:77], v[158:161], v[196:199], v[74:77]
	v_mfma_f32_16x16x32_bf16 v[70:73], v[150:153], v[204:207], v[70:73]
	v_mfma_f32_16x16x32_bf16 v[66:69], v[158:161], v[204:207], v[66:69]
	s_barrier
; #define PG8_STAGE(bufoff, gbase, voff) do { _Pragma("unroll") for (int _i = 0; _i < 2; ++_i) \
;         __builtin_amdgcn_global_load_lds((const unsigned*)((const char*)(gbase) + (voff)[_i]), (PG8_LAS unsigned*)(lds + (bufoff) + ldsw + _i * 8192), 16, 0, 0); } while (0)
; #define PG8_LDA(dst, b, h) do { _Pragma("unroll") for (int m = 0; m < 4; ++m) _Pragma("unroll") for (int k = 0; k < 2; ++k) dst[m][k] = *(const PG8_LAS bf16x8*)(lds + PG8_SA(b, h) + aoff + m * 2048 + k * 1024); } while (0)
; #define PG8_LDB(dst, b, h) do { _Pragma("unroll") for (int n = 0; n < 2; ++n) _Pragma("unroll") for (int k = 0; k < 2; ++k) dst[n][k] = *(const PG8_LAS bf16x8*)(lds + PG8_SB(b, h) + boff + n * 2048 + k * 1024); } while (0)
; #define PG8_MMA(ai, bj, At, Bt) do { __builtin_amdgcn_s_setprio(1); _Pragma("unroll") for (int m = 0; m < 4; ++m) _Pragma("unroll") for (int n = 0; n < 2; ++n) _Pragma("unroll") for (int k = 0; k < 2; ++k) \
;         acc[ai][bj][m][n] = __builtin_amdgcn_mfma_f32_16x16x32_bf16(Bt[n][k], At[m][k], acc[ai][bj][m][n], 0, 0, 0); __builtin_amdgcn_s_setprio(0); } while (0)
; #define PG8_WAIT_V(n) asm volatile("s_waitcnt vmcnt(" #n ")" ::: "memory")
; #define PG8_WAIT_L(n) asm volatile("s_waitcnt lgkmcnt(" #n ")" ::: "memory")
; #define PG8_BAR __builtin_amdgcn_s_barrier()
; #define PG8_SCHED __builtin_amdgcn_sched_barrier(0)
; template <class Epi, class Sched, bool ALIGN_EPI = false, bool SP2 = false>
; __device__ __forceinline__ void gemm_phase(PG8_LAS unsigned char* lds, const Gemm g, const Sched& S, const Epi& E) {
;     ...
;             PG8_LDB(B0, 0, 0); PG8_LDB(B1, 0, 1); PG8_SCHED; PG8_LDA(At, 0, 0); PG8_STAGE(PG8_SA(1, 1), a1 + hstep, voffA);
;             PG8_WAIT_V(8); PG8_WAIT_L(0); PG8_BAR; PG8_MMA(0, 0, At, B0); PG8_MMA(0, 1, At, B1); PG8_BAR; PG8_SCHED;
;     ...
;             PG8_LDA(At, 1, 1); PG8_STAGE(PG8_SB(1, 0), b3, voffB); PG8_STAGE(PG8_SB(1, 1), b3 + hstep, voffB); PG8_STAGE(PG8_SA(1, 0), a3, voffA);
;             PG8_WAIT_V(8); PG8_WAIT_L(0); PG8_BAR; PG8_MMA(1, 0, At, B0); PG8_MMA(1, 1, At, B1); PG8_BAR; PG8_SCHED;
	s_add_i32 s6, s11, s22
	v_lshl_add_u64 v[208:209], v[208:209], 0, s[12:13]
	s_mov_b32 m0, s6
	ds_read_b128 v[162:165], v214 offset:49152
	ds_read_b128 v[180:183], v214 offset:50176
	ds_read_b128 v[184:187], v214 offset:51200
	ds_read_b128 v[188:191], v214 offset:52224
	ds_read_b128 v[192:195], v214 offset:53248
	ds_read_b128 v[196:199], v214 offset:54272
	ds_read_b128 v[200:203], v214 offset:55296
	ds_read_b128 v[204:207], v214 offset:56320
	global_load_lds_dwordx4 v[208:209], off
	v_lshl_add_u64 v[208:209], v[216:217], 0, s[12:13]
	s_add_i32 m0, s6, 0x2000
	s_add_i32 s6, s86, s22
	global_load_lds_dwordx4 v[208:209], off
	v_lshl_add_u64 v[208:209], v[220:221], 0, s[12:13]
	s_mov_b32 m0, s6
	s_nop 0
	global_load_lds_dwordx4 v[208:209], off
	v_lshl_add_u64 v[208:209], v[224:225], 0, s[12:13]
	s_add_i32 m0, s6, 0x2000
	s_nop 0
	global_load_lds_dwordx4 v[208:209], off
	v_lshl_add_u64 v[208:209], v[228:229], 0, s[12:13]
	s_mov_b32 m0, s54
	s_nop 0
	global_load_lds_dwordx4 v[208:209], off
	v_lshl_add_u64 v[208:209], v[230:231], 0, s[12:13]
	s_mov_b32 m0, s55
	s_nop 0
	global_load_lds_dwordx4 v[208:209], off
	s_waitcnt vmcnt(8)
	s_waitcnt lgkmcnt(0)
	s_barrier
	s_waitcnt lgkmcnt(0)
	v_mfma_f32_16x16x32_bf16 v[62:65], v[130:133], v[162:165], v[62:65]
	v_mfma_f32_16x16x32_bf16 v[58:61], v[138:141], v[162:165], v[58:61]
	v_mfma_f32_16x16x32_bf16 v[54:57], v[130:133], v[184:187], v[54:57]
	v_mfma_f32_16x16x32_bf16 v[46:49], v[138:141], v[184:187], v[46:49]
	v_mfma_f32_16x16x32_bf16 v[38:41], v[130:133], v[192:195], v[38:41]
	v_mfma_f32_16x16x32_bf16 v[30:33], v[138:141], v[192:195], v[30:33]
	v_mfma_f32_16x16x32_bf16 v[22:25], v[130:133], v[200:203], v[22:25]
	v_mfma_f32_16x16x32_bf16 v[14:17], v[138:141], v[200:203], v[14:17]
	v_mfma_f32_16x16x32_bf16 v[62:65], v[134:137], v[180:183], v[62:65]
	v_mfma_f32_16x16x32_bf16 v[58:61], v[142:145], v[180:183], v[58:61]
	v_mfma_f32_16x16x32_bf16 v[54:57], v[134:137], v[188:191], v[54:57]
	v_mfma_f32_16x16x32_bf16 v[46:49], v[142:145], v[188:191], v[46:49]
	v_mfma_f32_16x16x32_bf16 v[38:41], v[134:137], v[196:199], v[38:41]
	v_mfma_f32_16x16x32_bf16 v[30:33], v[142:145], v[196:199], v[30:33]
	v_mfma_f32_16x16x32_bf16 v[22:25], v[134:137], v[204:207], v[22:25]
	v_mfma_f32_16x16x32_bf16 v[14:17], v[142:145], v[204:207], v[14:17]
	v_mfma_f32_16x16x32_bf16 v[50:53], v[146:149], v[162:165], v[50:53]
	v_mfma_f32_16x16x32_bf16 v[42:45], v[154:157], v[162:165], v[42:45]
	v_mfma_f32_16x16x32_bf16 v[34:37], v[146:149], v[184:187], v[34:37]
	v_mfma_f32_16x16x32_bf16 v[26:29], v[154:157], v[184:187], v[26:29]
	v_mfma_f32_16x16x32_bf16 v[18:21], v[146:149], v[192:195], v[18:21]
	v_mfma_f32_16x16x32_bf16 v[10:13], v[154:157], v[192:195], v[10:13]
	v_mfma_f32_16x16x32_bf16 v[6:9], v[146:149], v[200:203], v[6:9]
	v_mfma_f32_16x16x32_bf16 v[2:5], v[154:157], v[200:203], v[2:5]
	v_mfma_f32_16x16x32_bf16 v[50:53], v[150:153], v[180:183], v[50:53]
	v_mfma_f32_16x16x32_bf16 v[42:45], v[158:161], v[180:183], v[42:45]
	v_mfma_f32_16x16x32_bf16 v[34:37], v[150:153], v[188:191], v[34:37]
	v_mfma_f32_16x16x32_bf16 v[26:29], v[158:161], v[188:191], v[26:29]
	v_mfma_f32_16x16x32_bf16 v[18:21], v[150:153], v[196:199], v[18:21]
	v_mfma_f32_16x16x32_bf16 v[10:13], v[158:161], v[196:199], v[10:13]
	v_mfma_f32_16x16x32_bf16 v[6:9], v[150:153], v[204:207], v[6:9]
	v_mfma_f32_16x16x32_bf16 v[2:5], v[158:161], v[204:207], v[2:5]
	s_barrier
	s_add_u32 s2, s2, 0x100
	s_addc_u32 s3, s3, 0
	s_add_u32 s8, s8, 0x100
	s_addc_u32 s9, s9, 0
	s_cmp_ge_u32 s10, s56
	s_mov_b32 s6, s10
	s_cbranch_scc0 .LBB0_711
	s_branch .Lk_exit
.LBB0_711:
	s_add_i32 s10, s6, 2
	s_add_u32 s11, s2, 0x80
	s_addc_u32 s7, s3, 0
	s_waitcnt lgkmcnt(0)
	s_add_i32 s52, 0, 0x10000
	v_add_u32_e32 v0, s52, v211
	ds_read_b128 v[130:133], v0
	ds_read_b128 v[134:137], v0 offset:1024
	ds_read_b128 v[138:141], v0 offset:2048
	ds_read_b128 v[142:145], v0 offset:3072
	v_add_u32_e32 v0, s87, v211
	ds_read_b128 v[146:149], v0
	ds_read_b128 v[150:153], v0 offset:1024
	ds_read_b128 v[154:157], v0 offset:2048
	ds_read_b128 v[158:161], v0 offset:3072
	s_cmp_eq_u32 s57, s6
	s_cselect_b32 s6, s48, s11
	s_cselect_b32 s7, s49, s7
	s_cselect_b32 s47, s51, s9
	s_cselect_b32 s46, s50, s8
	v_lshl_add_u64 v[208:209], s[2:3], 0, v[174:175]
	s_add_i32 m0, s23, 0xc000
	ds_read_b128 v[162:165], v214
	ds_read_b128 v[180:183], v214 offset:1024
	ds_read_b128 v[184:187], v214 offset:2048
	ds_read_b128 v[188:191], v214 offset:3072
	ds_read_b128 v[192:195], v214 offset:4096
	ds_read_b128 v[196:199], v214 offset:5120
	ds_read_b128 v[200:203], v214 offset:6144
	ds_read_b128 v[204:207], v214 offset:7168
	global_load_lds_dwordx4 v[208:209], off
	v_lshl_add_u64 v[208:209], s[2:3], 0, v[176:177]
	s_add_i32 m0, s23, 0xe000
	s_nop 0
	global_load_lds_dwordx4 v[208:209], off
	s_waitcnt vmcnt(8)
	s_waitcnt lgkmcnt(0)
	s_barrier
; #define PG8_STAGE(bufoff, gbase, voff) do { _Pragma("unroll") for (int _i = 0; _i < 2; ++_i) \
;         __builtin_amdgcn_global_load_lds((const unsigned*)((const char*)(gbase) + (voff)[_i]), (PG8_LAS unsigned*)(lds + (bufoff) + ldsw + _i * 8192), 16, 0, 0); } while (0)
; #define PG8_LDA(dst, b, h) do { _Pragma("unroll") for (int m = 0; m < 4; ++m) _Pragma("unroll") for (int k = 0; k < 2; ++k) dst[m][k] = *(const PG8_LAS bf16x8*)(lds + PG8_SA(b, h) + aoff + m * 2048 + k * 1024); } while (0)
; #define PG8_LDB(dst, b, h) do { _Pragma("unroll") for (int n = 0; n < 2; ++n) _Pragma("unroll") for (int k = 0; k < 2; ++k) dst[n][k] = *(const PG8_LAS bf16x8*)(lds + PG8_SB(b, h) + boff + n * 2048 + k * 1024); } while (0)
; #define PG8_MMA(ai, bj, At, Bt) do { __builtin_amdgcn_s_setprio(1); _Pragma("unroll") for (int m = 0; m < 4; ++m) _Pragma("unroll") for (int n = 0; n < 2; ++n) _Pragma("unroll") for (int k = 0; k < 2; ++k) \
;         acc[ai][bj][m][n] = __builtin_amdgcn_mfma_f32_16x16x32_bf16(Bt[n][k], At[m][k], acc[ai][bj][m][n], 0, 0, 0); __builtin_amdgcn_s_setprio(0); } while (0)
; #define PG8_WAIT_V(n) asm volatile("s_waitcnt vmcnt(" #n ")" ::: "memory")
; #define PG8_WAIT_L(n) asm volatile("s_waitcnt lgkmcnt(" #n ")" ::: "memory")
; #define PG8_BAR __builtin_amdgcn_s_barrier()
; #define PG8_SCHED __builtin_amdgcn_sched_barrier(0)
; template <class Epi, class Sched, bool ALIGN_EPI = false, bool SP2 = false>
; __device__ __forceinline__ void gemm_phase(PG8_LAS unsigned char* lds, const Gemm g, const Sched& S, const Epi& E) {
;     ...
;             PG8_LDB(B0, 0, 0); PG8_LDB(B1, 0, 1); PG8_SCHED; PG8_LDA(At, 0, 0); PG8_STAGE(PG8_SA(1, 1), a1 + hstep, voffA);
;             PG8_WAIT_V(8); PG8_WAIT_L(0); PG8_BAR; PG8_MMA(0, 0, At, B0); PG8_MMA(0, 1, At, B1); PG8_BAR; PG8_SCHED;
;             PG8_LDA(At, 0, 1); PG8_STAGE(PG8_SB(0, 0), b2, voffB); PG8_STAGE(PG8_SB(0, 1), b2 + hstep, voffB); PG8_STAGE(PG8_SA(0, 0), a2, voffA);
;             PG8_WAIT_V(8); PG8_WAIT_L(0); PG8_BAR; PG8_MMA(1, 0, At, B0); PG8_MMA(1, 1, At, B1); PG8_BAR; PG8_SCHED;
	s_waitcnt lgkmcnt(0)
	v_mfma_f32_16x16x32_bf16 v[126:129], v[130:133], v[162:165], v[126:129]
	v_mfma_f32_16x16x32_bf16 v[122:125], v[138:141], v[162:165], v[122:125]
	v_mfma_f32_16x16x32_bf16 v[118:121], v[130:133], v[184:187], v[118:121]
	v_mfma_f32_16x16x32_bf16 v[110:113], v[138:141], v[184:187], v[110:113]
	v_mfma_f32_16x16x32_bf16 v[102:105], v[130:133], v[192:195], v[102:105]
	v_mfma_f32_16x16x32_bf16 v[94:97], v[138:141], v[192:195], v[94:97]
	v_mfma_f32_16x16x32_bf16 v[86:89], v[130:133], v[200:203], v[86:89]
	v_mfma_f32_16x16x32_bf16 v[78:81], v[138:141], v[200:203], v[78:81]
	v_mfma_f32_16x16x32_bf16 v[126:129], v[134:137], v[180:183], v[126:129]
	v_mfma_f32_16x16x32_bf16 v[122:125], v[142:145], v[180:183], v[122:125]
	v_mfma_f32_16x16x32_bf16 v[118:121], v[134:137], v[188:191], v[118:121]
	v_mfma_f32_16x16x32_bf16 v[110:113], v[142:145], v[188:191], v[110:113]
	v_mfma_f32_16x16x32_bf16 v[102:105], v[134:137], v[196:199], v[102:105]
	v_mfma_f32_16x16x32_bf16 v[94:97], v[142:145], v[196:199], v[94:97]
	v_mfma_f32_16x16x32_bf16 v[86:89], v[134:137], v[204:207], v[86:89]
	v_mfma_f32_16x16x32_bf16 v[78:81], v[142:145], v[204:207], v[78:81]
	v_mfma_f32_16x16x32_bf16 v[114:117], v[146:149], v[162:165], v[114:117]
	v_mfma_f32_16x16x32_bf16 v[106:109], v[154:157], v[162:165], v[106:109]
	v_mfma_f32_16x16x32_bf16 v[98:101], v[146:149], v[184:187], v[98:101]
	v_mfma_f32_16x16x32_bf16 v[90:93], v[154:157], v[184:187], v[90:93]
	v_mfma_f32_16x16x32_bf16 v[82:85], v[146:149], v[192:195], v[82:85]
	v_mfma_f32_16x16x32_bf16 v[74:77], v[154:157], v[192:195], v[74:77]
	v_mfma_f32_16x16x32_bf16 v[70:73], v[146:149], v[200:203], v[70:73]
	v_mfma_f32_16x16x32_bf16 v[66:69], v[154:157], v[200:203], v[66:69]
	v_mfma_f32_16x16x32_bf16 v[114:117], v[150:153], v[180:183], v[114:117]
	v_mfma_f32_16x16x32_bf16 v[106:109], v[158:161], v[180:183], v[106:109]
	v_mfma_f32_16x16x32_bf16 v[98:101], v[150:153], v[188:191], v[98:101]
	v_mfma_f32_16x16x32_bf16 v[90:93], v[158:161], v[188:191], v[90:93]
	v_mfma_f32_16x16x32_bf16 v[82:85], v[150:153], v[196:199], v[82:85]
	v_mfma_f32_16x16x32_bf16 v[74:77], v[158:161], v[196:199], v[74:77]
	v_mfma_f32_16x16x32_bf16 v[70:73], v[150:153], v[204:207], v[70:73]
	v_mfma_f32_16x16x32_bf16 v[66:69], v[158:161], v[204:207], v[66:69]
	s_barrier
	s_add_i32 s11, s52, s22
	v_lshl_add_u64 v[208:209], s[46:47], 0, v[168:169]
	s_mov_b32 m0, s11
	ds_read_b128 v[162:165], v214 offset:16384
	ds_read_b128 v[180:183], v214 offset:17408
	ds_read_b128 v[184:187], v214 offset:18432
	ds_read_b128 v[188:191], v214 offset:19456
	ds_read_b128 v[192:195], v214 offset:20480
	ds_read_b128 v[196:199], v214 offset:21504
	ds_read_b128 v[200:203], v214 offset:22528
	ds_read_b128 v[204:207], v214 offset:23552
	global_load_lds_dwordx4 v[208:209], off
	s_add_i32 m0, s11, 0x2000
	v_lshl_add_u64 v[216:217], s[46:47], 0, v[172:173]
	s_add_u32 s46, s46, s96
	s_addc_u32 s47, s47, 0
	s_add_i32 s11, s87, s22
	global_load_lds_dwordx4 v[216:217], off
	v_lshl_add_u64 v[220:221], s[46:47], 0, v[168:169]
	s_mov_b32 m0, s11
	v_lshl_add_u64 v[224:225], s[46:47], 0, v[172:173]
	global_load_lds_dwordx4 v[220:221], off
	s_add_i32 m0, s11, 0x2000
	v_lshl_add_u64 v[228:229], s[6:7], 0, v[166:167]
	global_load_lds_dwordx4 v[224:225], off
	s_mov_b32 m0, s23
	v_lshl_add_u64 v[230:231], s[6:7], 0, v[170:171]
	global_load_lds_dwordx4 v[228:229], off
	s_mov_b32 m0, s24
	s_nop 0
	global_load_lds_dwordx4 v[230:231], off
	s_waitcnt vmcnt(8)
	s_waitcnt lgkmcnt(0)
	s_barrier
	s_waitcnt lgkmcnt(0)
	v_mfma_f32_16x16x32_bf16 v[62:65], v[130:133], v[162:165], v[62:65]
	v_mfma_f32_16x16x32_bf16 v[58:61], v[138:141], v[162:165], v[58:61]
	v_mfma_f32_16x16x32_bf16 v[54:57], v[130:133], v[184:187], v[54:57]
	v_mfma_f32_16x16x32_bf16 v[46:49], v[138:141], v[184:187], v[46:49]
	v_mfma_f32_16x16x32_bf16 v[38:41], v[130:133], v[192:195], v[38:41]
	v_mfma_f32_16x16x32_bf16 v[30:33], v[138:141], v[192:195], v[30:33]
	v_mfma_f32_16x16x32_bf16 v[22:25], v[130:133], v[200:203], v[22:25]
	v_mfma_f32_16x16x32_bf16 v[14:17], v[138:141], v[200:203], v[14:17]
	v_mfma_f32_16x16x32_bf16 v[62:65], v[134:137], v[180:183], v[62:65]
	v_mfma_f32_16x16x32_bf16 v[58:61], v[142:145], v[180:183], v[58:61]
	v_mfma_f32_16x16x32_bf16 v[54:57], v[134:137], v[188:191], v[54:57]
	v_mfma_f32_16x16x32_bf16 v[46:49], v[142:145], v[188:191], v[46:49]
	v_mfma_f32_16x16x32_bf16 v[38:41], v[134:137], v[196:199], v[38:41]
	v_mfma_f32_16x16x32_bf16 v[30:33], v[142:145], v[196:199], v[30:33]
	v_mfma_f32_16x16x32_bf16 v[22:25], v[134:137], v[204:207], v[22:25]
	v_mfma_f32_16x16x32_bf16 v[14:17], v[142:145], v[204:207], v[14:17]
	v_mfma_f32_16x16x32_bf16 v[50:53], v[146:149], v[162:165], v[50:53]
	v_mfma_f32_16x16x32_bf16 v[42:45], v[154:157], v[162:165], v[42:45]
	v_mfma_f32_16x16x32_bf16 v[34:37], v[146:149], v[184:187], v[34:37]
	v_mfma_f32_16x16x32_bf16 v[26:29], v[154:157], v[184:187], v[26:29]
	v_mfma_f32_16x16x32_bf16 v[18:21], v[146:149], v[192:195], v[18:21]
	v_mfma_f32_16x16x32_bf16 v[10:13], v[154:157], v[192:195], v[10:13]
	v_mfma_f32_16x16x32_bf16 v[6:9], v[146:149], v[200:203], v[6:9]
	v_mfma_f32_16x16x32_bf16 v[2:5], v[154:157], v[200:203], v[2:5]
	v_mfma_f32_16x16x32_bf16 v[50:53], v[150:153], v[180:183], v[50:53]
	v_mfma_f32_16x16x32_bf16 v[42:45], v[158:161], v[180:183], v[42:45]
	v_mfma_f32_16x16x32_bf16 v[34:37], v[150:153], v[188:191], v[34:37]
	v_mfma_f32_16x16x32_bf16 v[26:29], v[158:161], v[188:191], v[26:29]
	v_mfma_f32_16x16x32_bf16 v[18:21], v[150:153], v[196:199], v[18:21]
	v_mfma_f32_16x16x32_bf16 v[10:13], v[158:161], v[196:199], v[10:13]
	v_mfma_f32_16x16x32_bf16 v[6:9], v[150:153], v[204:207], v[6:9]
	v_mfma_f32_16x16x32_bf16 v[2:5], v[158:161], v[204:207], v[2:5]
	s_barrier
; #define PG8_STAGE(bufoff, gbase, voff) do { _Pragma("unroll") for (int _i = 0; _i < 2; ++_i) \
;         __builtin_amdgcn_global_load_lds((const unsigned*)((const char*)(gbase) + (voff)[_i]), (PG8_LAS unsigned*)(lds + (bufoff) + ldsw + _i * 8192), 16, 0, 0); } while (0)
; #define PG8_LDA(dst, b, h) do { _Pragma("unroll") for (int m = 0; m < 4; ++m) _Pragma("unroll") for (int k = 0; k < 2; ++k) dst[m][k] = *(const PG8_LAS bf16x8*)(lds + PG8_SA(b, h) + aoff + m * 2048 + k * 1024); } while (0)
; #define PG8_LDB(dst, b, h) do { _Pragma("unroll") for (int n = 0; n < 2; ++n) _Pragma("unroll") for (int k = 0; k < 2; ++k) dst[n][k] = *(const PG8_LAS bf16x8*)(lds + PG8_SB(b, h) + boff + n * 2048 + k * 1024); } while (0)
; #define PG8_MMA(ai, bj, At, Bt) do { __builtin_amdgcn_s_setprio(1); _Pragma("unroll") for (int m = 0; m < 4; ++m) _Pragma("unroll") for (int n = 0; n < 2; ++n) _Pragma("unroll") for (int k = 0; k < 2; ++k) \
;         acc[ai][bj][m][n] = __builtin_amdgcn_mfma_f32_16x16x32_bf16(Bt[n][k], At[m][k], acc[ai][bj][m][n], 0, 0, 0); __builtin_amdgcn_s_setprio(0); } while (0)
; #define PG8_WAIT_V(n) asm volatile("s_waitcnt vmcnt(" #n ")" ::: "memory")
; #define PG8_WAIT_L(n) asm volatile("s_waitcnt lgkmcnt(" #n ")" ::: "memory")
; #define PG8_BAR __builtin_amdgcn_s_barrier()
; #define PG8_SCHED __builtin_amdgcn_sched_barrier(0)
; template <class Epi, class Sched, bool ALIGN_EPI = false, bool SP2 = false>
; __device__ __forceinline__ void gemm_phase(PG8_LAS unsigned char* lds, const Gemm g, const Sched& S, const Epi& E) {
;     ...
;             PG8_LDB(B0, 1, 0); PG8_LDB(B1, 1, 1); PG8_SCHED; PG8_LDA(At, 1, 0); PG8_STAGE(PG8_SA(0, 1), a2 + hstep, voffA);
;             PG8_WAIT_V(8); PG8_WAIT_L(0); PG8_BAR; PG8_MMA(0, 0, At, B0); PG8_MMA(0, 1, At, B1); PG8_BAR; PG8_SCHED;
;             PG8_LDA(At, 1, 1); PG8_STAGE(PG8_SB(1, 0), b3, voffB); PG8_STAGE(PG8_SB(1, 1), b3 + hstep, voffB); PG8_STAGE(PG8_SA(1, 0), a3, voffA);
;             PG8_WAIT_V(8); PG8_WAIT_L(0); PG8_BAR; PG8_MMA(1, 0, At, B0); PG8_MMA(1, 1, At, B1); PG8_BAR; PG8_SCHED;
	s_add_i32 s11, 0, 0x18000
	v_add_u32_e32 v0, s11, v211
	ds_read_b128 v[130:133], v0
	ds_read_b128 v[134:137], v0 offset:1024
	ds_read_b128 v[138:141], v0 offset:2048
	ds_read_b128 v[142:145], v0 offset:3072
	v_add_u32_e32 v0, s86, v211
	ds_read_b128 v[146:149], v0
	ds_read_b128 v[150:153], v0 offset:1024
	ds_read_b128 v[154:157], v0 offset:2048
	ds_read_b128 v[158:161], v0 offset:3072
	s_add_u32 s6, s6, s96
	s_addc_u32 s7, s7, 0
	s_mov_b32 m0, s25
	v_lshl_add_u64 v[238:239], s[6:7], 0, v[166:167]
	ds_read_b128 v[162:165], v214 offset:32768
	ds_read_b128 v[180:183], v214 offset:33792
	ds_read_b128 v[184:187], v214 offset:34816
	ds_read_b128 v[188:191], v214 offset:35840
	ds_read_b128 v[192:195], v214 offset:36864
	ds_read_b128 v[196:199], v214 offset:37888
	ds_read_b128 v[200:203], v214 offset:38912
	ds_read_b128 v[204:207], v214 offset:39936
	global_load_lds_dwordx4 v[238:239], off
	v_lshl_add_u64 v[238:239], s[6:7], 0, v[170:171]
	s_mov_b32 m0, s27
	s_nop 0
	global_load_lds_dwordx4 v[238:239], off
	s_waitcnt vmcnt(8)
	s_waitcnt lgkmcnt(0)
	s_barrier
	s_waitcnt lgkmcnt(0)
	v_mfma_f32_16x16x32_bf16 v[126:129], v[130:133], v[162:165], v[126:129]
	v_mfma_f32_16x16x32_bf16 v[122:125], v[138:141], v[162:165], v[122:125]
	v_mfma_f32_16x16x32_bf16 v[118:121], v[130:133], v[184:187], v[118:121]
	v_mfma_f32_16x16x32_bf16 v[110:113], v[138:141], v[184:187], v[110:113]
	v_mfma_f32_16x16x32_bf16 v[102:105], v[130:133], v[192:195], v[102:105]
	v_mfma_f32_16x16x32_bf16 v[94:97], v[138:141], v[192:195], v[94:97]
	v_mfma_f32_16x16x32_bf16 v[86:89], v[130:133], v[200:203], v[86:89]
	v_mfma_f32_16x16x32_bf16 v[78:81], v[138:141], v[200:203], v[78:81]
	v_mfma_f32_16x16x32_bf16 v[126:129], v[134:137], v[180:183], v[126:129]
	v_mfma_f32_16x16x32_bf16 v[122:125], v[142:145], v[180:183], v[122:125]
	v_mfma_f32_16x16x32_bf16 v[118:121], v[134:137], v[188:191], v[118:121]
	v_mfma_f32_16x16x32_bf16 v[110:113], v[142:145], v[188:191], v[110:113]
	v_mfma_f32_16x16x32_bf16 v[102:105], v[134:137], v[196:199], v[102:105]
	v_mfma_f32_16x16x32_bf16 v[94:97], v[142:145], v[196:199], v[94:97]
	v_mfma_f32_16x16x32_bf16 v[86:89], v[134:137], v[204:207], v[86:89]
	v_mfma_f32_16x16x32_bf16 v[78:81], v[142:145], v[204:207], v[78:81]
	v_mfma_f32_16x16x32_bf16 v[114:117], v[146:149], v[162:165], v[114:117]
	v_mfma_f32_16x16x32_bf16 v[106:109], v[154:157], v[162:165], v[106:109]
	v_mfma_f32_16x16x32_bf16 v[98:101], v[146:149], v[184:187], v[98:101]
	v_mfma_f32_16x16x32_bf16 v[90:93], v[154:157], v[184:187], v[90:93]
	v_mfma_f32_16x16x32_bf16 v[82:85], v[146:149], v[192:195], v[82:85]
	v_mfma_f32_16x16x32_bf16 v[74:77], v[154:157], v[192:195], v[74:77]
	v_mfma_f32_16x16x32_bf16 v[70:73], v[146:149], v[200:203], v[70:73]
	v_mfma_f32_16x16x32_bf16 v[66:69], v[154:157], v[200:203], v[66:69]
	v_mfma_f32_16x16x32_bf16 v[114:117], v[150:153], v[180:183], v[114:117]
	v_mfma_f32_16x16x32_bf16 v[106:109], v[158:161], v[180:183], v[106:109]
	v_mfma_f32_16x16x32_bf16 v[98:101], v[150:153], v[188:191], v[98:101]
	v_mfma_f32_16x16x32_bf16 v[90:93], v[158:161], v[188:191], v[90:93]
	v_mfma_f32_16x16x32_bf16 v[82:85], v[150:153], v[196:199], v[82:85]
	v_mfma_f32_16x16x32_bf16 v[74:77], v[158:161], v[196:199], v[74:77]
	v_mfma_f32_16x16x32_bf16 v[70:73], v[150:153], v[204:207], v[70:73]
	v_mfma_f32_16x16x32_bf16 v[66:69], v[158:161], v[204:207], v[66:69]
	s_barrier
	s_add_i32 s6, s11, s22
	v_lshl_add_u64 v[208:209], v[208:209], 0, s[12:13]
	s_mov_b32 m0, s6
	ds_read_b128 v[162:165], v214 offset:49152
	ds_read_b128 v[180:183], v214 offset:50176
	ds_read_b128 v[184:187], v214 offset:51200
	ds_read_b128 v[188:191], v214 offset:52224
	ds_read_b128 v[192:195], v214 offset:53248
	ds_read_b128 v[196:199], v214 offset:54272
	ds_read_b128 v[200:203], v214 offset:55296
	ds_read_b128 v[204:207], v214 offset:56320
	global_load_lds_dwordx4 v[208:209], off
	v_lshl_add_u64 v[208:209], v[216:217], 0, s[12:13]
	s_add_i32 m0, s6, 0x2000
	s_add_i32 s6, s86, s22
	global_load_lds_dwordx4 v[208:209], off
	v_lshl_add_u64 v[208:209], v[220:221], 0, s[12:13]
	s_mov_b32 m0, s6
	s_nop 0
	global_load_lds_dwordx4 v[208:209], off
	v_lshl_add_u64 v[208:209], v[224:225], 0, s[12:13]
	s_add_i32 m0, s6, 0x2000
	s_nop 0
	global_load_lds_dwordx4 v[208:209], off
	v_lshl_add_u64 v[208:209], v[228:229], 0, s[12:13]
	s_mov_b32 m0, s54
	s_nop 0
	global_load_lds_dwordx4 v[208:209], off
	v_lshl_add_u64 v[208:209], v[230:231], 0, s[12:13]
	s_mov_b32 m0, s55
	s_nop 0
	global_load_lds_dwordx4 v[208:209], off
	s_waitcnt vmcnt(8)
	s_waitcnt lgkmcnt(0)
	s_barrier
	s_waitcnt lgkmcnt(0)
	v_mfma_f32_16x16x32_bf16 v[62:65], v[130:133], v[162:165], v[62:65]
	v_mfma_f32_16x16x32_bf16 v[58:61], v[138:141], v[162:165], v[58:61]
	v_mfma_f32_16x16x32_bf16 v[54:57], v[130:133], v[184:187], v[54:57]
	v_mfma_f32_16x16x32_bf16 v[46:49], v[138:141], v[184:187], v[46:49]
	v_mfma_f32_16x16x32_bf16 v[38:41], v[130:133], v[192:195], v[38:41]
	v_mfma_f32_16x16x32_bf16 v[30:33], v[138:141], v[192:195], v[30:33]
	v_mfma_f32_16x16x32_bf16 v[22:25], v[130:133], v[200:203], v[22:25]
	v_mfma_f32_16x16x32_bf16 v[14:17], v[138:141], v[200:203], v[14:17]
	v_mfma_f32_16x16x32_bf16 v[62:65], v[134:137], v[180:183], v[62:65]
	v_mfma_f32_16x16x32_bf16 v[58:61], v[142:145], v[180:183], v[58:61]
	v_mfma_f32_16x16x32_bf16 v[54:57], v[134:137], v[188:191], v[54:57]
	v_mfma_f32_16x16x32_bf16 v[46:49], v[142:145], v[188:191], v[46:49]
	v_mfma_f32_16x16x32_bf16 v[38:41], v[134:137], v[196:199], v[38:41]
	v_mfma_f32_16x16x32_bf16 v[30:33], v[142:145], v[196:199], v[30:33]
	v_mfma_f32_16x16x32_bf16 v[22:25], v[134:137], v[204:207], v[22:25]
	v_mfma_f32_16x16x32_bf16 v[14:17], v[142:145], v[204:207], v[14:17]
	v_mfma_f32_16x16x32_bf16 v[50:53], v[146:149], v[162:165], v[50:53]
	v_mfma_f32_16x16x32_bf16 v[42:45], v[154:157], v[162:165], v[42:45]
	v_mfma_f32_16x16x32_bf16 v[34:37], v[146:149], v[184:187], v[34:37]
	v_mfma_f32_16x16x32_bf16 v[26:29], v[154:157], v[184:187], v[26:29]
	v_mfma_f32_16x16x32_bf16 v[18:21], v[146:149], v[192:195], v[18:21]
	v_mfma_f32_16x16x32_bf16 v[10:13], v[154:157], v[192:195], v[10:13]
	v_mfma_f32_16x16x32_bf16 v[6:9], v[146:149], v[200:203], v[6:9]
	v_mfma_f32_16x16x32_bf16 v[2:5], v[154:157], v[200:203], v[2:5]
	v_mfma_f32_16x16x32_bf16 v[50:53], v[150:153], v[180:183], v[50:53]
	v_mfma_f32_16x16x32_bf16 v[42:45], v[158:161], v[180:183], v[42:45]
	v_mfma_f32_16x16x32_bf16 v[34:37], v[150:153], v[188:191], v[34:37]
	v_mfma_f32_16x16x32_bf16 v[26:29], v[158:161], v[188:191], v[26:29]
	v_mfma_f32_16x16x32_bf16 v[18:21], v[150:153], v[196:199], v[18:21]
	v_mfma_f32_16x16x32_bf16 v[10:13], v[158:161], v[196:199], v[10:13]
	v_mfma_f32_16x16x32_bf16 v[6:9], v[150:153], v[204:207], v[6:9]
	v_mfma_f32_16x16x32_bf16 v[2:5], v[158:161], v[204:207], v[2:5]
	s_barrier
	s_add_u32 s2, s2, 0x100
	s_addc_u32 s3, s3, 0
	s_add_u32 s8, s8, 0x100
	s_addc_u32 s9, s9, 0
	s_cmp_ge_u32 s10, s56
	s_mov_b32 s6, s10
	s_cbranch_scc0 .LBB0_711

; #define PG8_WAIT_V(n) asm volatile("s_waitcnt vmcnt(" #n ")" ::: "memory")
; #define PG8_BAR __builtin_amdgcn_s_barrier()
; template <class Epi, class Sched, bool ALIGN_EPI = false, bool SP2 = false>
; __device__ __forceinline__ void gemm_phase(PG8_LAS unsigned char* lds, const Gemm g, const Sched& S, const Epi& E) {
;     ...
;     PG8_WAIT_V(0);
;     if constexpr (!ALIGN_EPI) { if (wr == 0) PG8_BAR; }
;     PG8_BAR;
.LBB0_769:
	s_setprio 0
	s_waitcnt vmcnt(0)
	s_barrier
